# GEMM unit table lookup: both LDS reads of the next-unit entry issued together (one wait instead of two dependent round trips)
# speedup vs baseline: 1.0036x; 1.0036x over previous
; #define LAS __attribute__((address_space(3)))
;     __device__ __forceinline__ bool next(int i, Unit& u) const {
;         if (i >= UTAB_MAX) return false;
;         const LAS unsigned* e = (const LAS unsigned*)(lds + UTAB_OFF + i * 32);
;         const u32x4 lo = *(const LAS u32x4*)e, hi = *(const LAS u32x4*)(e + 4);
;         const unsigned nt = __builtin_amdgcn_readfirstlane(hi.x); if (nt == 0u) return false;
;         const unsigned a0 = __builtin_amdgcn_readfirstlane(lo.x), a1 = __builtin_amdgcn_readfirstlane(lo.y), b0 = __builtin_amdgcn_readfirstlane(lo.z), b1 = __builtin_amdgcn_readfirstlane(lo.w);
;         u.A = (const char*)(uintptr_t)(((unsigned long long)a1 << 32) | a0); u.B = (const char*)(uintptr_t)(((unsigned long long)b1 << 32) | b0);
;         u.nt = (int)nt; u.pm = (int)__builtin_amdgcn_readfirstlane(hi.y); u.pn = (int)__builtin_amdgcn_readfirstlane(hi.z);
;         const unsigned eb = __builtin_amdgcn_readfirstlane(hi.w); u.em = (int)(eb & 255u); u.br = (int)(eb >> 8); return true;
.LBB0_412:
	s_mov_b32 s19, s62
	s_add_i32 s62, s62, 1
	s_cmp_gt_u32 s19, 62
	s_mov_b64 s[44:45], 0
	s_cbranch_scc1 .LBB0_415
	s_lshl_b32 s19, s62, 5
	s_add_i32 s42, s19, 0
	s_add_i32 s19, s42, 0x20010
	v_mov_b32_e32 v8, s19
	ds_read_b128 v[8:11], v8
	s_add_i32 s43, s42, 0x20000
	v_mov_b32_e32 v12, s43
	ds_read_b128 v[12:15], v12
	s_waitcnt lgkmcnt(0)
	v_readfirstlane_b32 s19, v8
	s_cmp_eq_u32 s19, 0
	s_cbranch_scc1 .LBB0_415
	v_readfirstlane_b32 s42, v11
	v_readfirstlane_b32 s63, v9
	v_readfirstlane_b32 s64, v10
	s_and_b32 s66, s42, 0xff
	s_waitcnt lgkmcnt(0)
	v_readfirstlane_b32 s8, v12
	v_readfirstlane_b32 s9, v13
	v_readfirstlane_b32 s10, v14
	v_readfirstlane_b32 s11, v15
	s_lshr_b32 s65, s42, 8
	s_mov_b64 s[44:45], -1
	s_mov_b32 s67, s19
